# attention combine: 16 LDS partial-result reads issued together with counted lgkmcnt waits
# baseline (speedup 1.0000x reference)
.LBB0_700:
	v_mul_f32_e32 v2, 0x3fb8aa3b, v161
	v_exp_f32_e32 v2, v2
	v_mov_b32_e32 v36, v187
	v_mov_b32_e32 v37, v183
	v_readlane_b32 s4, v254, 60
	v_sub_f32_e32 v2, v165, v2
	v_permlane32_swap_b32_e32 v187, v36
	v_permlane32_swap_b32_e32 v183, v37
	v_add_f32_e32 v2, s4, v2
	v_add_f32_e32 v36, v187, v36
	v_add_f32_e32 v37, v183, v37
	v_cndmask_b32_e64 v2, v2, 1.0, s[38:39]
	v_cndmask_b32_e64 v38, v36, v37, s[38:39]
	v_div_scale_f32 v39, s[4:5], v38, v38, v2
	v_rcp_f32_e32 v40, v39
	v_readlane_b32 s4, v254, 1
	v_cndmask_b32_e64 v44, v64, v80, s[38:39]
	v_cndmask_b32_e64 v45, v63, v79, s[38:39]
	v_fma_f32 v41, -v39, v40, 1.0
	v_fmac_f32_e32 v40, v41, v40
	v_div_scale_f32 v41, vcc, v2, v38, v2
	v_mul_f32_e32 v42, v41, v40
	v_fma_f32 v43, -v39, v42, v41
	v_fmac_f32_e32 v42, v43, v40
	v_fma_f32 v39, -v39, v42, v41
	v_div_fmas_f32 v39, v39, v40, v42
	v_div_fixup_f32 v38, v39, v38, v2
	v_lshlrev_b32_e32 v39, 2, v163
	v_cndmask_b32_e64 v41, v67, v83, s[38:39]
	v_cndmask_b32_e64 v42, v66, v82, s[38:39]
	v_add_u32_e32 v40, s4, v39
	v_mul_f32_e32 v42, v42, v38
	v_mul_f32_e32 v41, v41, v38
	v_cndmask_b32_e64 v43, v65, v81, s[38:39]
	v_cndmask_b32_e64 v46, v62, v78, s[38:39]
	v_cndmask_b32_e64 v47, v61, v77, s[38:39]
	v_cndmask_b32_e64 v48, v60, v76, s[38:39]
	v_cndmask_b32_e64 v49, v59, v75, s[38:39]
	v_cndmask_b32_e64 v50, v58, v74, s[38:39]
	v_cndmask_b32_e64 v51, v57, v73, s[38:39]
	v_cndmask_b32_e64 v84, v56, v72, s[38:39]
	v_cndmask_b32_e64 v85, v55, v71, s[38:39]
	v_cndmask_b32_e64 v86, v54, v70, s[38:39]
	v_cndmask_b32_e64 v87, v53, v69, s[38:39]
	v_cndmask_b32_e64 v88, v52, v68, s[38:39]
	ds_write2st64_b32 v40, v42, v41 offset0:14 offset1:15
	v_cndmask_b32_e64 v41, v35, v19, s[38:39]
	v_cndmask_b32_e64 v42, v34, v18, s[38:39]
	v_mul_f32_e32 v88, v88, v38
	v_mul_f32_e32 v87, v87, v38
	v_mul_f32_e32 v86, v86, v38
	v_mul_f32_e32 v85, v85, v38
	v_mul_f32_e32 v84, v84, v38
	v_mul_f32_e32 v51, v51, v38
	v_mul_f32_e32 v50, v50, v38
	v_mul_f32_e32 v49, v49, v38
	v_mul_f32_e32 v48, v48, v38
	v_mul_f32_e32 v47, v47, v38
	v_mul_f32_e32 v46, v46, v38
	v_mul_f32_e32 v45, v45, v38
	v_mul_f32_e32 v44, v44, v38
	v_mul_f32_e32 v43, v43, v38
	v_mul_f32_e32 v42, v42, v38
	v_cndmask_b32_e64 v36, v37, v36, s[38:39]
	v_mul_f32_e32 v37, v41, v38
	ds_write2st64_b32 v40, v88, v87 offset1:1
	ds_write2st64_b32 v40, v86, v85 offset0:2 offset1:3
	ds_write2st64_b32 v40, v84, v51 offset0:4 offset1:5
	ds_write2st64_b32 v40, v50, v49 offset0:6 offset1:7
	ds_write2st64_b32 v40, v48, v47 offset0:8 offset1:9
	ds_write2st64_b32 v40, v46, v45 offset0:10 offset1:11
	ds_write2st64_b32 v40, v44, v43 offset0:12 offset1:13
	v_cndmask_b32_e64 v43, v33, v17, s[38:39]
	v_cndmask_b32_e64 v44, v32, v16, s[38:39]
	v_cndmask_b32_e64 v45, v31, v15, s[38:39]
	v_cndmask_b32_e64 v46, v30, v14, s[38:39]
	v_cndmask_b32_e64 v47, v29, v13, s[38:39]
	v_cndmask_b32_e64 v48, v28, v12, s[38:39]
	v_cndmask_b32_e64 v49, v27, v11, s[38:39]
	v_cndmask_b32_e64 v50, v26, v10, s[38:39]
	v_cndmask_b32_e64 v51, v25, v9, s[38:39]
	v_cndmask_b32_e64 v84, v24, v8, s[38:39]
	v_cndmask_b32_e64 v85, v23, v7, s[38:39]
	v_cndmask_b32_e64 v86, v22, v6, s[38:39]
	v_cndmask_b32_e64 v87, v21, v5, s[38:39]
	v_cndmask_b32_e64 v88, v20, v4, s[38:39]
	ds_write2st64_b32 v40, v42, v37 offset0:30 offset1:31
	v_div_scale_f32 v37, s[4:5], v36, v36, v2
	v_mul_f32_e32 v88, v88, v38
	v_mul_f32_e32 v87, v87, v38
	v_mul_f32_e32 v86, v86, v38
	v_mul_f32_e32 v85, v85, v38
	v_mul_f32_e32 v84, v84, v38
	v_mul_f32_e32 v51, v51, v38
	v_mul_f32_e32 v50, v50, v38
	v_mul_f32_e32 v49, v49, v38
	v_mul_f32_e32 v48, v48, v38
	v_mul_f32_e32 v47, v47, v38
	v_mul_f32_e32 v46, v46, v38
	v_mul_f32_e32 v45, v45, v38
	v_mul_f32_e32 v44, v44, v38
	v_mul_f32_e32 v43, v43, v38
	v_rcp_f32_e32 v38, v37
	ds_write2st64_b32 v40, v88, v87 offset0:16 offset1:17
	ds_write2st64_b32 v40, v86, v85 offset0:18 offset1:19
	ds_write2st64_b32 v40, v84, v51 offset0:20 offset1:21
	ds_write2st64_b32 v40, v50, v49 offset0:22 offset1:23
	ds_write2st64_b32 v40, v48, v47 offset0:24 offset1:25
	ds_write2st64_b32 v40, v46, v45 offset0:26 offset1:27
	ds_write2st64_b32 v40, v44, v43 offset0:28 offset1:29
	v_fma_f32 v40, -v37, v38, 1.0
	v_fmac_f32_e32 v38, v40, v38
	v_div_scale_f32 v40, vcc, v2, v36, v2
	v_readlane_b32 s4, v254, 2
	v_mul_f32_e32 v41, v40, v38
	s_waitcnt lgkmcnt(0)
	v_add_u32_e32 v84, s4, v39
	s_barrier
	ds_read2st64_b32 v[114:115], v84 offset1:1
	ds_read2st64_b32 v[116:117], v84 offset0:2 offset1:3
	ds_read2st64_b32 v[118:119], v84 offset0:4 offset1:5
	ds_read2st64_b32 v[120:121], v84 offset0:6 offset1:7
	ds_read2st64_b32 v[122:123], v84 offset0:8 offset1:9
	ds_read2st64_b32 v[124:125], v84 offset0:10 offset1:11
	ds_read2st64_b32 v[126:127], v84 offset0:12 offset1:13
	ds_read2st64_b32 v[128:129], v84 offset0:14 offset1:15
	ds_read2st64_b32 v[130:131], v84 offset0:16 offset1:17
	ds_read2st64_b32 v[132:133], v84 offset0:18 offset1:19
	ds_read2st64_b32 v[134:135], v84 offset0:20 offset1:21
	ds_read2st64_b32 v[136:137], v84 offset0:22 offset1:23
	ds_read2st64_b32 v[138:139], v84 offset0:24 offset1:25
	ds_read2st64_b32 v[140:141], v84 offset0:26 offset1:27
	ds_read2st64_b32 v[142:143], v84 offset0:28 offset1:29
	ds_read_b32 v146, v84 offset:7680
	v_fma_f32 v42, -v37, v41, v40
	v_cndmask_b32_e64 v51, v69, v53, s[38:39]
	v_cndmask_b32_e64 v50, v68, v52, s[38:39]
	v_fmac_f32_e32 v41, v42, v38
	v_fma_f32 v37, -v37, v41, v40
	v_div_fmas_f32 v37, v37, v38, v41
	v_div_fixup_f32 v2, v37, v36, v2
	v_cndmask_b32_e64 v43, v77, v61, s[38:39]
	v_cndmask_b32_e64 v42, v76, v60, s[38:39]
	s_waitcnt lgkmcnt(15)
	v_pk_fma_f32 v[60:61], v[50:51], v[2:3], v[114:115] op_sel_hi:[1,0,1] neg_lo:[0,0,1] neg_hi:[0,0,1]
	v_cndmask_b32_e64 v49, v71, v55, s[38:39]
	v_cndmask_b32_e64 v48, v70, v54, s[38:39]
	v_cndmask_b32_e64 v39, v81, v65, s[38:39]
	v_cndmask_b32_e64 v38, v80, v64, s[38:39]
	s_waitcnt lgkmcnt(14)
	v_pk_fma_f32 v[64:65], v[48:49], v[2:3], v[116:117] op_sel_hi:[1,0,1] neg_lo:[0,0,1] neg_hi:[0,0,1]
	v_cndmask_b32_e64 v47, v73, v57, s[38:39]
	v_cndmask_b32_e64 v46, v72, v56, s[38:39]
	v_cndmask_b32_e64 v41, v79, v63, s[38:39]
	v_cndmask_b32_e64 v40, v78, v62, s[38:39]
	s_waitcnt lgkmcnt(13)
	v_pk_fma_f32 v[62:63], v[46:47], v[2:3], v[118:119] op_sel_hi:[1,0,1] neg_lo:[0,0,1] neg_hi:[0,0,1]
	v_cndmask_b32_e64 v45, v75, v59, s[38:39]
	v_cndmask_b32_e64 v44, v74, v58, s[38:39]
	v_cndmask_b32_e64 v37, v83, v67, s[38:39]
	v_cndmask_b32_e64 v36, v82, v66, s[38:39]
	s_waitcnt lgkmcnt(12)
	v_pk_fma_f32 v[66:67], v[44:45], v[2:3], v[120:121] op_sel_hi:[1,0,1] neg_lo:[0,0,1] neg_hi:[0,0,1]
	v_cndmask_b32_e64 v5, v5, v21, s[38:39]
	v_cndmask_b32_e64 v4, v4, v20, s[38:39]
	v_cndmask_b32_e64 v7, v7, v23, s[38:39]
	v_cndmask_b32_e64 v6, v6, v22, s[38:39]
	s_waitcnt lgkmcnt(11)
	v_pk_fma_f32 v[56:57], v[42:43], v[2:3], v[122:123] op_sel_hi:[1,0,1] neg_lo:[0,0,1] neg_hi:[0,0,1]
	v_cndmask_b32_e64 v9, v9, v25, s[38:39]
	v_cndmask_b32_e64 v8, v8, v24, s[38:39]
	v_cndmask_b32_e64 v11, v11, v27, s[38:39]
	v_cndmask_b32_e64 v10, v10, v26, s[38:39]
	s_waitcnt lgkmcnt(10)
	v_pk_fma_f32 v[58:59], v[40:41], v[2:3], v[124:125] op_sel_hi:[1,0,1] neg_lo:[0,0,1] neg_hi:[0,0,1]
	v_cndmask_b32_e64 v13, v13, v29, s[38:39]
	v_cndmask_b32_e64 v12, v12, v28, s[38:39]
	v_cndmask_b32_e64 v15, v15, v31, s[38:39]
	v_cndmask_b32_e64 v14, v14, v30, s[38:39]
	s_waitcnt lgkmcnt(9)
	v_pk_fma_f32 v[46:47], v[38:39], v[2:3], v[126:127] op_sel_hi:[1,0,1] neg_lo:[0,0,1] neg_hi:[0,0,1]
	v_cndmask_b32_e64 v17, v17, v33, s[38:39]
	v_cndmask_b32_e64 v16, v16, v32, s[38:39]
	v_readlane_b32 s4, v253, 63
	v_cndmask_b32_e64 v18, v18, v34, s[38:39]
	s_waitcnt lgkmcnt(8)
	v_pk_fma_f32 v[54:55], v[36:37], v[2:3], v[128:129] op_sel_hi:[1,0,1] neg_lo:[0,0,1] neg_hi:[0,0,1]
	v_readlane_b32 s5, v254, 0
	s_and_b64 vcc, exec, s[4:5]
	s_waitcnt lgkmcnt(7)
	v_pk_fma_f32 v[38:39], v[4:5], v[2:3], v[130:131] op_sel_hi:[1,0,1] neg_lo:[0,0,1] neg_hi:[0,0,1]
	s_waitcnt lgkmcnt(6)
	v_pk_fma_f32 v[40:41], v[6:7], v[2:3], v[132:133] op_sel_hi:[1,0,1] neg_lo:[0,0,1] neg_hi:[0,0,1]
	s_waitcnt lgkmcnt(5)
	v_pk_fma_f32 v[36:37], v[8:9], v[2:3], v[134:135] op_sel_hi:[1,0,1] neg_lo:[0,0,1] neg_hi:[0,0,1]
	s_waitcnt lgkmcnt(4)
	v_pk_fma_f32 v[42:43], v[10:11], v[2:3], v[136:137] op_sel_hi:[1,0,1] neg_lo:[0,0,1] neg_hi:[0,0,1]
	s_waitcnt lgkmcnt(3)
	v_pk_fma_f32 v[48:49], v[12:13], v[2:3], v[138:139] op_sel_hi:[1,0,1] neg_lo:[0,0,1] neg_hi:[0,0,1]
	s_waitcnt lgkmcnt(2)
	v_pk_fma_f32 v[50:51], v[14:15], v[2:3], v[140:141] op_sel_hi:[1,0,1] neg_lo:[0,0,1] neg_hi:[0,0,1]
	s_waitcnt lgkmcnt(1)
	v_pk_fma_f32 v[44:45], v[16:17], v[2:3], v[142:143] op_sel_hi:[1,0,1] neg_lo:[0,0,1] neg_hi:[0,0,1]
	s_waitcnt lgkmcnt(0)
	v_fma_f32 v52, v18, v2, -v146
	s_cbranch_vccnz .LBB0_624
	v_mov_b64_e32 v[4:5], v[20:21]
	v_mov_b64_e32 v[156:157], v[158:159]
	v_mov_b64_e32 v[6:7], v[22:23]
	v_mov_b64_e32 v[8:9], v[24:25]
	v_mov_b64_e32 v[10:11], v[26:27]
	v_mov_b64_e32 v[12:13], v[28:29]
	v_mov_b64_e32 v[14:15], v[30:31]
	v_mov_b64_e32 v[16:17], v[32:33]
	v_mov_b64_e32 v[18:19], v[34:35]
	s_branch .LBB0_625
